# Fourier out-projection: A sub-tiles kept chunk-major in LDS as well, so every 16 lanes of a staging load read 256 contiguous bytes
# speedup vs baseline: 1.0102x; 1.0037x over previous
;     ...
;     for (int i = 0; i < 2; ++i) { int R, C; stage_rc(tid * 16 + i * 8192, R, C); const int Rb = Epi::PERM ? ((R & ~31) + perm32(R & 31)) : R;
;         voffA[i] = (unsigned)(R * (LDA ? LDA : K) + C) * 2u; voffB[i] = (unsigned)(Rb * K + C) * 2u; }
.Lop_fourier:
	v_lshrrev_b32_e32 v246, 7, v0
	v_and_b32_e32 v247, 15, v0
	v_lshl_or_b32 v246, v246, 4, v247
	v_lshlrev_b32_e32 v246, 4, v246
	v_bfe_u32 v247, v0, 6, 1
	v_bfe_u32 v248, v0, 4, 2
	v_lshl_or_b32 v247, v247, 2, v248
	v_lshl_or_b32 v246, v247, 18, v246
	v_add_u32_e32 v248, 0x400, v246
	v_mov_b32_e32 v244, 0x200000
	s_mov_b32 s101, 0x200000
	v_writelane_b32 v255, s101, 40
	s_mov_b32 s101, 0x400000
	v_writelane_b32 v255, s101, 41
	s_movk_i32 s101, 0x800

;     ...
;     const int tid = tid_l, wid = __builtin_amdgcn_readfirstlane(tid >> 6), lane = tid & 63, wr = wid >> 2, wc = wid & 3, fr = lane & 15, fq = lane >> 4;
;     int K_l = g.K; asm volatile("" : "+s"(K_l));
;     const int K = K_l, nt = K / BK;
;     const bf16_t* gA = g.A; const bf16_t* gB = g.Bt; asm volatile("" : "+s"(gA), "+s"(gB));
;     unsigned voffA[2], voffB[2];
; #pragma unroll
;     for (int i = 0; i < 2; ++i) { int R, C; stage_rc(tid * 16 + i * 8192, R, C); const int Rb = Epi::PERM ? ((R & ~31) + perm32(R & 31)) : R;
;         voffA[i] = (unsigned)(R * (LDA ? LDA : K) + C) * 2u; voffB[i] = (unsigned)(Rb * K + C) * 2u; }
;     const size_t kstep = (size_t)(BK * 2);
;     const size_t hstepB = (size_t)HALF * K * 2, hstepA = LDA ? (size_t)HALF * LDA * 2 : hstepB;
;     const size_t tstepA = 2 * hstepA, tstepB = 2 * hstepB; constexpr size_t acolB = (size_t)ACOL * 2;
;     const unsigned ldsw = (unsigned)wid * 1024u;
;     const int aoff = lds_byte(wr * 64 + fr, fq * 8), boff = lds_byte(wc * 32 + fr, fq * 8);
.LBB0_505:
	v_bfe_u32 v16, v2, 4, 2
	s_lshr_b32 s11, s11, 26
	v_mov_b32_e32 v131, v167
	v_and_b32_e32 v228, 15, v2
	s_add_i32 s11, s10, s11
	v_lshlrev_b32_e32 v3, 4, v16
	v_lshlrev_b32_e32 v2, 2, v2
	v_lshl_add_u64 v[8:9], s[12:13], 0, v[166:167]
	v_lshl_add_u64 v[10:11], s[12:13], 0, v[130:131]
	s_and_b32 s12, s16, 3
	s_ashr_i32 s13, s11, 6
	v_lshl_or_b32 v3, v228, 6, v3
	s_lshl_b32 s11, s17, 13
	v_and_b32_e32 v2, 32, v2
	v_lshl_add_u64 v[4:5], s[6:7], 0, v[166:167]
	v_bitop3_b32 v17, v3, s11, v2 bitop3:0xde
	s_lshl_b32 s11, s12, 12
	v_lshl_add_u64 v[6:7], s[6:7], 0, v[130:131]
	v_bitop3_b32 v229, v3, s11, v2 bitop3:0xde
	s_add_i32 m0, s2, 0x18000
	v_lshl_add_u64 v[2:3], v[4:5], 0, s[62:63]
	v_lshl_add_u64 v[12:13], s[8:9], 0, v[246:247]
	s_lshl_b32 s16, s17, 6
	s_waitcnt vmcnt(2)
	s_barrier
	global_load_lds_dwordx4 v[2:3], off
	v_lshl_add_u64 v[2:3], v[6:7], 0, s[62:63]
	s_add_i32 m0, s2, 0x1a000
	s_add_i32 s17, s2, 0x8000
	v_lshl_add_u64 v[14:15], s[8:9], 0, v[248:249]
	global_load_lds_dwordx4 v[2:3], off
	v_lshl_add_u64 v[2:3], v[12:13], 0, v[244:245]
	s_mov_b32 m0, s17
	s_add_i32 s18, s2, 0xa000
	global_load_lds_dwordx4 v[2:3], off
	v_lshl_add_u64 v[2:3], v[14:15], 0, v[244:245]
	s_mov_b32 m0, s18
	v_cmp_eq_u32_e64 s[38:39], 0, v16
	global_load_lds_dwordx4 v[2:3], off
	s_add_i32 m0, s2, 0x1c000
	v_lshl_add_u64 v[2:3], v[8:9], 0, s[62:63]
	global_load_lds_dwordx4 v[2:3], off
	v_lshl_add_u64 v[2:3], v[10:11], 0, s[62:63]
	s_add_i32 m0, s2, 0x1e000
	s_cmp_gt_i32 s10, 63
	global_load_lds_dwordx4 v[2:3], off
	s_waitcnt vmcnt(6)
	s_cselect_b64 s[88:89], -1, 0
	s_add_i32 s19, s13, -2
	s_cmpk_lt_u32 s20, 0x100
	v_lshlrev_b32_e32 v2, 2, v16
	v_readlane_b32 s10, v254, 25
	s_cselect_b64 s[90:91], -1, 0
	v_lshl_or_b32 v230, s12, 5, v2
	s_mov_b32 s20, 0
	v_add_u32_e32 v132, s101, v248
	v_mov_b32_e32 v133, 0
	v_add_u32_e32 v134, s101, v246
	v_mov_b32_e32 v135, 0
	v_add_u32_e32 v231, 0, v17
	s_cmpk_lg_u32 s101, 0x800
	s_cbranch_scc1 .Lop_rd_done
	v_lshlrev_b32_e32 v231, 4, v228
	v_lshl_or_b32 v231, v16, 8, v231
	s_lshl_b32 s11, s16, 7
	v_or_b32_e32 v231, s11, v231
.Lop_rd_done:
	v_readlane_b32 s23, v254, 13
	s_mov_b32 s24, s10
	s_barrier
	v_readlane_b32 s11, v254, 26
	s_branch .LBB0_508
